# layer-1 FFN2 weight conversion moved out of the layer-0 final LN phase into the idle gap of the layer-1 branch-GEMM phase
# speedup vs baseline: 1.0032x; 1.0032x over previous
.LBB0_227:
	s_or_b64 exec, exec, s[10:11]
	s_andn2_b64 vcc, exec, s[14:15]
	s_cbranch_vccnz .LBB0_233
	v_readlane_b32 s4, v251, 5
	v_readlane_b32 s5, v251, 6
	s_andn2_b64 vcc, exec, s[4:5]
	s_mov_b64 s[8:9], -1
	s_cbranch_vccnz .LBB0_231
	v_readlane_b32 s4, v251, 7
	v_readlane_b32 s5, v251, 8
	s_andn2_b64 vcc, exec, s[4:5]
	s_add_i32 s2, s62, 0x210
	s_cbranch_vccnz .LBB0_230
	s_cmpk_gt_i32 s62, 0x87
	s_cbranch_scc1 .LBB0_230
	s_branch .LBB0_243

.LBB0_1497:
	v_readlane_b32 s4, v254, 20
	v_readlane_b32 s5, v254, 21
	s_and_b64 s[4:5], s[40:41], s[4:5]
	s_cmp_eq_u32 s56, 6
	s_cselect_b64 s[8:9], -1, 0
	v_readlane_b32 s10, v254, 25
	s_and_b64 s[8:9], s[4:5], s[8:9]
	v_readlane_b32 s11, v254, 26
	s_and_b64 s[8:9], s[92:93], s[8:9]
	s_andn2_b64 vcc, exec, s[8:9]
	s_mov_b32 s2, s62
	s_mul_i32 s33, s34, 24
	s_cbranch_vccz .LBB0_1529

.LBB0_1528:
	s_mul_hi_i32 s19, s14, s8
	s_mul_i32 s18, s14, s8
	s_ashr_i32 s9, s8, 31
	s_lshl_b64 s[18:19], s[18:19], 2
	v_ashrrev_i32_e32 v4, 5, v2
	s_add_u32 s16, s16, s18
	v_and_b32_e32 v5, -2, v4
	s_addc_u32 s17, s17, s19
	v_max_i32_e32 v152, 0, v22
	v_add_u32_e32 v6, 16, v5
	v_lshl_add_u64 v[0:1], v[152:153], 2, s[16:17]
	v_mad_i64_i32 v[6:7], s[16:17], s14, v6, 0
	v_lshl_add_u64 v[6:7], v[6:7], 2, v[0:1]
	global_load_dword v6, v[6:7], off
	v_add_u32_e32 v7, 17, v5
	v_mad_i64_i32 v[8:9], s[16:17], s14, v7, 0
	v_lshl_add_u64 v[8:9], v[8:9], 2, v[0:1]
	global_load_dword v7, v[8:9], off
	v_add_u32_e32 v8, 32, v5
	v_mad_i64_i32 v[8:9], s[16:17], s14, v8, 0
	v_lshl_add_u64 v[8:9], v[8:9], 2, v[0:1]
	global_load_dword v8, v[8:9], off
	v_add_u32_e32 v9, 33, v5
	v_mad_i64_i32 v[10:11], s[16:17], s14, v9, 0
	v_lshl_add_u64 v[10:11], v[10:11], 2, v[0:1]
	global_load_dword v9, v[10:11], off
	v_add_u32_e32 v10, 48, v5
	v_mad_i64_i32 v[10:11], s[16:17], s14, v10, 0
	v_lshl_add_u64 v[10:11], v[10:11], 2, v[0:1]
	global_load_dword v10, v[10:11], off
	v_add_u32_e32 v11, 49, v5
	v_mad_i64_i32 v[14:15], s[16:17], s14, v11, 0
	v_lshl_add_u64 v[14:15], v[14:15], 2, v[0:1]
	v_add_u32_e32 v12, 64, v5
	global_load_dword v11, v[14:15], off
	v_mad_i64_i32 v[14:15], s[16:17], s14, v12, 0
	v_lshl_add_u64 v[14:15], v[14:15], 2, v[0:1]
	global_load_dword v12, v[14:15], off
	v_add_u32_e32 v14, 0x41, v5
	v_mad_i64_i32 v[14:15], s[16:17], s14, v14, 0
	v_lshl_add_u64 v[14:15], v[14:15], 2, v[0:1]
	global_load_dword v14, v[14:15], off
	v_add_u32_e32 v15, 0x50, v5
	v_mad_i64_i32 v[16:17], s[16:17], s14, v15, 0
	v_lshl_add_u64 v[16:17], v[16:17], 2, v[0:1]
	global_load_dword v15, v[16:17], off
	v_add_u32_e32 v16, 0x51, v5
	v_mad_i64_i32 v[16:17], s[16:17], s14, v16, 0
	v_lshl_add_u64 v[16:17], v[16:17], 2, v[0:1]
	global_load_dword v16, v[16:17], off
	v_add_u32_e32 v17, 0x60, v5
	v_mad_i64_i32 v[18:19], s[16:17], s14, v17, 0
	v_lshl_add_u64 v[18:19], v[18:19], 2, v[0:1]
	global_load_dword v17, v[18:19], off
	v_add_u32_e32 v18, 0x61, v5
	v_mad_i64_i32 v[18:19], s[16:17], s14, v18, 0
	v_lshl_add_u64 v[18:19], v[18:19], 2, v[0:1]
	global_load_dword v18, v[18:19], off
	v_add_u32_e32 v19, 0x70, v5
	v_mad_i64_i32 v[20:21], s[16:17], s14, v19, 0
	v_lshl_add_u64 v[20:21], v[20:21], 2, v[0:1]
	global_load_dword v19, v[20:21], off
	v_add_u32_e32 v20, 0x71, v5
	v_mad_i64_i32 v[20:21], s[16:17], s14, v20, 0
	v_lshl_add_u64 v[20:21], v[20:21], 2, v[0:1]
	global_load_dword v20, v[20:21], off
	v_add_u32_e32 v21, 0x80, v5
	v_mad_i64_i32 v[24:25], s[16:17], s14, v21, 0
	v_lshl_add_u64 v[24:25], v[24:25], 2, v[0:1]
	v_add_u32_e32 v23, 0x81, v5
	global_load_dword v21, v[24:25], off
	v_mad_i64_i32 v[24:25], s[16:17], s14, v23, 0
	v_lshl_add_u64 v[24:25], v[24:25], 2, v[0:1]
	global_load_dword v23, v[24:25], off
	v_add_u32_e32 v24, 0x90, v5
	v_mad_i64_i32 v[24:25], s[16:17], s14, v24, 0
	v_lshl_add_u64 v[24:25], v[24:25], 2, v[0:1]
	global_load_dword v24, v[24:25], off
	v_add_u32_e32 v25, 0x91, v5
	v_mad_i64_i32 v[26:27], s[16:17], s14, v25, 0
	v_lshl_add_u64 v[26:27], v[26:27], 2, v[0:1]
	global_load_dword v25, v[26:27], off
	v_add_u32_e32 v26, 0xa0, v5
	v_mad_i64_i32 v[26:27], s[16:17], s14, v26, 0
	v_lshl_add_u64 v[26:27], v[26:27], 2, v[0:1]
	global_load_dword v28, v[26:27], off
	v_add_u32_e32 v26, 0xa1, v5
	v_mad_i64_i32 v[26:27], s[16:17], s14, v26, 0
	v_lshl_add_u64 v[26:27], v[26:27], 2, v[0:1]
	global_load_dword v29, v[26:27], off
	v_add_u32_e32 v26, 0xb0, v5
	v_mad_i64_i32 v[26:27], s[16:17], s14, v26, 0
	v_lshl_add_u64 v[26:27], v[26:27], 2, v[0:1]
	global_load_dword v30, v[26:27], off
	v_add_u32_e32 v26, 0xb1, v5
	v_mad_i64_i32 v[26:27], s[16:17], s14, v26, 0
	v_lshl_add_u64 v[26:27], v[26:27], 2, v[0:1]
	global_load_dword v31, v[26:27], off
	v_add_u32_e32 v26, 0xc0, v5
	v_mad_i64_i32 v[26:27], s[16:17], s14, v26, 0
	v_lshl_add_u64 v[26:27], v[26:27], 2, v[0:1]
	global_load_dword v32, v[26:27], off
	v_add_u32_e32 v26, 0xc1, v5
	v_mad_i64_i32 v[26:27], s[16:17], s14, v26, 0
	v_lshl_add_u64 v[26:27], v[26:27], 2, v[0:1]
	global_load_dword v33, v[26:27], off
	v_add_u32_e32 v26, 0xd0, v5
	v_mad_i64_i32 v[26:27], s[16:17], s14, v26, 0
	v_lshl_add_u64 v[26:27], v[26:27], 2, v[0:1]
	global_load_dword v34, v[26:27], off
	v_add_u32_e32 v26, 0xd1, v5
	v_mad_i64_i32 v[26:27], s[16:17], s14, v26, 0
	v_lshl_add_u64 v[26:27], v[26:27], 2, v[0:1]
	global_load_dword v35, v[26:27], off
	v_add_u32_e32 v26, 0xe0, v5
	v_mad_i64_i32 v[26:27], s[16:17], s14, v26, 0
	v_lshl_add_u64 v[26:27], v[26:27], 2, v[0:1]
	global_load_dword v36, v[26:27], off
	v_add_u32_e32 v26, 0xe1, v5
	v_mad_i64_i32 v[26:27], s[16:17], s14, v26, 0
	v_lshl_add_u64 v[26:27], v[26:27], 2, v[0:1]
	global_load_dword v37, v[26:27], off
	v_add_u32_e32 v26, 0xf0, v5
	v_mad_i64_i32 v[26:27], s[16:17], s14, v26, 0
	v_lshl_add_u64 v[26:27], v[26:27], 2, v[0:1]
	global_load_dword v38, v[26:27], off
	v_add_u32_e32 v26, 0xf1, v5
	v_mad_i64_i32 v[26:27], s[16:17], s14, v26, 0
	v_lshl_add_u64 v[26:27], v[26:27], 2, v[0:1]
	global_load_dword v39, v[26:27], off
	v_mad_i64_i32 v[26:27], s[16:17], s14, v5, 0
	v_lshl_add_u64 v[26:27], v[26:27], 2, v[0:1]
	v_cmp_gt_i32_e32 vcc, 0, v22
	global_load_dword v22, v[26:27], off
	v_or_b32_e32 v26, 1, v4
	v_mad_i64_i32 v[26:27], s[14:15], s14, v26, 0
	v_lshl_add_u64 v[0:1], v[26:27], 2, v[0:1]
	global_load_dword v0, v[0:1], off
	v_mul_u32_u24_e32 v13, 0x210, v13
	v_lshlrev_b32_e32 v1, 1, v5
	s_waitcnt vmcnt(0)
	v_cndmask_b32_e64 v5, v6, 0, vcc
	v_cndmask_b32_e64 v6, v7, 0, vcc
	v_add3_u32 v1, 0, v13, v1
	v_cvt_pk_bf16_f32 v5, v5, v6
	v_cndmask_b32_e64 v6, v11, 0, vcc
	s_lshl_b64 s[8:9], s[8:9], 1
	s_add_u32 s8, s12, s8
	s_addc_u32 s9, s13, s9
	v_cndmask_b32_e64 v22, v22, 0, vcc
	v_cndmask_b32_e64 v0, v0, 0, vcc
	v_cvt_pk_bf16_f32 v0, v22, v0
	ds_write2_b32 v1, v0, v5 offset1:8
	v_cndmask_b32_e64 v0, v8, 0, vcc
	v_cndmask_b32_e64 v5, v9, 0, vcc
	v_cvt_pk_bf16_f32 v0, v0, v5
	v_cndmask_b32_e64 v5, v10, 0, vcc
	v_cvt_pk_bf16_f32 v5, v5, v6
	ds_write2_b32 v1, v0, v5 offset0:16 offset1:24
	v_cndmask_b32_e64 v0, v12, 0, vcc
	v_cndmask_b32_e64 v5, v14, 0, vcc
	v_cvt_pk_bf16_f32 v0, v0, v5
	v_cndmask_b32_e64 v5, v15, 0, vcc
	v_cndmask_b32_e64 v6, v16, 0, vcc
	v_cvt_pk_bf16_f32 v5, v5, v6
	ds_write2_b32 v1, v0, v5 offset0:32 offset1:40
	v_cndmask_b32_e64 v0, v17, 0, vcc
	v_cndmask_b32_e64 v5, v18, 0, vcc
	v_cvt_pk_bf16_f32 v0, v0, v5
	v_cndmask_b32_e64 v5, v19, 0, vcc
	v_cndmask_b32_e64 v6, v20, 0, vcc
	v_cvt_pk_bf16_f32 v5, v5, v6
	ds_write2_b32 v1, v0, v5 offset0:48 offset1:56
	v_cndmask_b32_e64 v0, v21, 0, vcc
	v_cndmask_b32_e64 v5, v23, 0, vcc
	v_cvt_pk_bf16_f32 v0, v0, v5
	v_cndmask_b32_e64 v5, v24, 0, vcc
	v_cndmask_b32_e64 v6, v25, 0, vcc
	v_cvt_pk_bf16_f32 v5, v5, v6
	ds_write2_b32 v1, v0, v5 offset0:64 offset1:72
	v_cndmask_b32_e64 v0, v28, 0, vcc
	v_cndmask_b32_e64 v5, v29, 0, vcc
	v_cvt_pk_bf16_f32 v0, v0, v5
	v_cndmask_b32_e64 v5, v30, 0, vcc
	v_cndmask_b32_e64 v6, v31, 0, vcc
	v_cvt_pk_bf16_f32 v5, v5, v6
	ds_write2_b32 v1, v0, v5 offset0:80 offset1:88
	v_cndmask_b32_e64 v0, v32, 0, vcc
	v_cndmask_b32_e64 v5, v33, 0, vcc
	v_cvt_pk_bf16_f32 v0, v0, v5
	v_cndmask_b32_e64 v5, v34, 0, vcc
	v_cndmask_b32_e64 v6, v35, 0, vcc
	v_cvt_pk_bf16_f32 v5, v5, v6
	ds_write2_b32 v1, v0, v5 offset0:96 offset1:104
	v_cndmask_b32_e64 v0, v36, 0, vcc
	v_cndmask_b32_e64 v5, v37, 0, vcc
	v_cvt_pk_bf16_f32 v0, v0, v5
	v_cndmask_b32_e64 v5, v38, 0, vcc
	v_cndmask_b32_e64 v6, v39, 0, vcc
	v_cvt_pk_bf16_f32 v5, v5, v6
	ds_write2_b32 v1, v0, v5 offset0:112 offset1:120
	v_lshlrev_b32_e32 v0, 4, v2
	v_and_b32_e32 v152, 0x1f0, v0
	v_add_u32_e32 v0, 0, v152
	v_lshl_add_u64 v[10:11], s[8:9], 0, v[152:153]
	v_mad_u64_u32 v[6:7], s[8:9], v4, s69, v[0:1]
	s_waitcnt lgkmcnt(0)
	s_barrier
	ds_read_b128 v[6:9], v6
	v_add_u32_e32 v1, v3, v4
	v_mad_i64_i32 v[4:5], s[8:9], s10, v1, 0
	v_add_u32_e32 v1, 0x200, v2
	v_lshl_add_u64 v[4:5], v[4:5], 1, v[10:11]
	v_ashrrev_i32_e32 v1, 5, v1
	s_waitcnt lgkmcnt(0)
	global_store_dwordx4 v[4:5], v[6:9], off
	v_mad_u64_u32 v[4:5], s[8:9], v1, s69, v[0:1]
	ds_read_b128 v[4:7], v4
	v_add_u32_e32 v1, v3, v1
	v_mad_i64_i32 v[8:9], s[8:9], s10, v1, 0
	v_add_u32_e32 v1, 0x400, v2
	v_lshl_add_u64 v[8:9], v[8:9], 1, v[10:11]
	v_ashrrev_i32_e32 v1, 5, v1
	s_waitcnt lgkmcnt(0)
	global_store_dwordx4 v[8:9], v[4:7], off
	s_nop 1
	v_mad_u64_u32 v[4:5], s[8:9], v1, s69, v[0:1]
	ds_read_b128 v[4:7], v4
	v_add_u32_e32 v1, v3, v1
	v_mad_i64_i32 v[8:9], s[8:9], s10, v1, 0
	v_add_u32_e32 v1, 0x600, v2
	v_ashrrev_i32_e32 v2, 5, v1
	v_lshl_add_u64 v[8:9], v[8:9], 1, v[10:11]
	v_mad_u64_u32 v[0:1], s[8:9], v2, s69, v[0:1]
	s_waitcnt lgkmcnt(0)
	global_store_dwordx4 v[8:9], v[4:7], off
	ds_read_b128 v[4:7], v0
	v_add_u32_e32 v0, v3, v2
	v_mad_i64_i32 v[0:1], s[8:9], s10, v0, 0
	s_add_i32 s8, s2, 0x80
	v_readlane_b32 s98, v254, 22
	v_lshl_add_u64 v[0:1], v[0:1], 1, v[10:11]
	s_cmp_eq_u32 s98, 0
	s_movk_i32 s99, 0x190
	s_cselect_b32 s98, 0x280, s99
	s_cmp_lt_i32 s2, s98
	s_mov_b32 s2, s8
	s_waitcnt lgkmcnt(0)
	global_store_dwordx4 v[0:1], v[4:7], off
	s_barrier
	s_cbranch_scc0 .LBB0_1498

.LBB0_1553:
	s_and_b64 vcc, exec, s[12:13]
	s_cbranch_vccz .LBB0_1527
	v_readfirstlane_b32 s8, v0
	v_lshlrev_b32_e32 v0, 1, v2
	v_lshrrev_b32_e32 v1, 2, v2
	v_and_b32_e32 v3, 35, v2
	s_mov_b64 s[18:19], -1
	s_cmp_eq_u32 s23, 1
	v_and_b32_e32 v0, 24, v0
	v_and_or_b32 v1, v1, 4, v3
	s_cbranch_scc1 .LBB0_1556
	v_readlane_b32 s98, v254, 22
	s_nop 1
	s_cmp_eq_u32 s98, 0
	s_cselect_b64 s[14:15], s[14:15], 0
	s_lshl_b32 s9, s22, 4
	s_lshl_b32 s8, s22, 8
	s_and_b32 s20, s9, 0xffffffc0
	s_and_b32 s8, s8, 0x300
	s_and_b64 s[12:13], exec, s[14:15]
	s_movk_i32 s12, 0x60
	s_cselect_b32 s12, 0x50, s12
	s_add_u32 s12, s0, s12
	s_addc_u32 s13, s1, 0
	s_load_dwordx2 s[12:13], s[12:13], 0x0
	s_mov_b64 s[18:19], 0
	s_waitcnt lgkmcnt(0)
	s_add_u32 s16, s12, 0x1600000
	s_addc_u32 s17, s13, 0
	s_lshl_b32 s13, s22, 3
	s_and_b32 s9, s9, 64
	s_bfe_i32 s12, s22, 0x10003
	s_and_b32 s13, s13, 0xffffff80
	v_or3_b32 v3, v1, v0, s9
	s_and_b32 s12, s12, 0xb00
	v_or_b32_e32 v3, s13, v3
	v_add_u32_e32 v22, s12, v3
	s_and_b64 s[12:13], exec, s[14:15]
	s_cselect_b32 s9, 0, 0x1080000
	s_add_u32 s12, s46, s9
	s_addc_u32 s13, s47, 0
	v_mov_b32_e32 v3, s20
.LBB0_1556:
	s_andn2_b64 vcc, exec, s[18:19]
	s_cbranch_vccnz .LBB0_1558
	v_readlane_b32 s98, v254, 22
	s_nop 1
	s_cmp_eq_u32 s98, 0
	s_cselect_b64 s[10:11], s[10:11], 0
	s_mul_hi_i32 s8, s22, 0x2e8ba2e9
	s_lshr_b32 s9, s8, 31
	s_ashr_i32 s8, s8, 1
	s_add_i32 s8, s8, s9
	s_mul_i32 s9, s8, 11
	s_sub_i32 s9, s22, s9
	s_lshl_b32 s18, s8, 6
	s_lshl_b32 s8, s9, 8
	s_and_b64 s[12:13], s[10:11], exec
	s_movk_i32 s9, 0x68
	s_cselect_b32 s9, 0x58, s9
	s_add_u32 s12, s0, s9
	s_addc_u32 s13, s1, 0
	s_load_dwordx2 s[12:13], s[12:13], 0x0
	s_mov_b32 s9, 0xb00000
	v_or3_b32 v22, v1, v0, s18
	s_mov_b64 s[14:15], 0x400
	v_mov_b32_e32 v3, s18
	s_waitcnt lgkmcnt(0)
	s_add_u32 s16, s12, 0xb00000
	s_addc_u32 s17, s13, 0
	s_and_b64 s[10:11], s[10:11], exec
	s_cselect_b32 s9, s9, 0x1b80000
	s_add_u32 s12, s46, s9
	s_addc_u32 s13, s47, 0
	s_mov_b64 s[10:11], 0xb00
	s_branch .LBB0_1528
